# P6 fftconv: loop-top wait no longer waits for the previous item's 4 stores (vmcnt(4) + one-time vmcnt(0) on the prologue path); on top of P0 de-serialisation and the guarded final
# baseline (speedup 1.0000x reference)
; __device__ __forceinline__ int lnd(int x) { asm volatile("" : "+v"(x)); return x; }
; __device__ __forceinline__ void fftconv_phase(const Args& a, LAS unsigned char* lds, int bid, int G, int tid) {
;     ...
;     const int vid = (G % 8 == 0) ? (bid >> 3) + (G >> 3) * (bid & 7) : bid;
;     v4u nx[4];
;     { FftItem I; int r0, r1, r2, r3, f1; if (vid < 4608) { fft_item(vid, UCT, I, r0, r1, r2, r3, f1); const int t8 = 8 * lnd(tid);
;         nx[0] = *(const v4u*)(I.base + r0 + t8); nx[1] = *(const v4u*)(I.base + r1 + t8); nx[2] = *(const v4u*)(I.base + r2 + t8); nx[3] = *(const v4u*)(I.base + r3 + t8); } }
.LBB0_844:
	s_waitcnt lgkmcnt(0)
	s_add_u32 s50, s10, 0x2a000000
	s_addc_u32 s51, s11, 0
	s_add_u32 s52, s10, 0x3000000
	s_mul_i32 s1, s13, 0x30000
	s_mul_hi_u32 s3, s12, 0x30000
	s_addc_u32 s53, s11, 0
	s_add_i32 s3, s3, s1
	s_mul_i32 s1, s12, 0x30000
	s_add_u32 s12, s50, s1
	s_mov_b32 s9, 0
	s_addc_u32 s13, s51, s3
	s_lshl_b64 s[10:11], s[8:9], 1
	s_add_u32 s10, s12, s10
	s_mov_b32 s5, s9
	s_addc_u32 s11, s13, s11
	s_lshl_b64 s[4:5], s[4:5], 1
	v_mov_b32_e32 v0, v34
	s_add_u32 s4, s12, s4
	s_mov_b32 s3, s9
	s_addc_u32 s5, s13, s5
	s_lshl_b64 s[2:3], s[2:3], 1
	v_lshlrev_b32_e32 v0, 3, v0
	s_add_u32 s2, s12, s2
	s_mov_b32 s1, s9
	v_ashrrev_i32_e32 v1, 31, v0
	s_addc_u32 s3, s13, s3
	s_lshl_b64 s[0:1], s[0:1], 1
	v_lshlrev_b64 v[8:9], 1, v[0:1]
	s_add_u32 s0, s12, s0
	v_lshl_add_u64 v[10:11], s[10:11], 0, v[8:9]
	v_lshl_add_u64 v[12:13], s[4:5], 0, v[8:9]
	v_lshl_add_u64 v[16:17], s[2:3], 0, v[8:9]
	s_addc_u32 s1, s13, s1
	global_load_dwordx4 v[0:3], v[10:11], off
	global_load_dwordx4 v[4:7], v[12:13], off
	v_lshl_add_u64 v[18:19], s[0:1], 0, v[8:9]
	global_load_dwordx4 v[8:11], v[16:17], off
	global_load_dwordx4 v[12:15], v[18:19], off
	s_mov_b32 s12, 0x3f6c835e
	s_mov_b32 s8, s9
	s_mov_b32 s10, 0x3f7b14be
	s_mov_b32 s13, 0x3ec3ef15
	s_mov_b32 s14, 0x3f3504f3
	s_lshl_b32 s54, s70, 14
	s_movk_i32 s55, 0x4000
	s_mov_b32 s56, 0xc000
	s_movk_i32 s57, 0x3000
	v_mov_b64_e32 v[100:101], s[8:9]
	s_movk_i32 s58, 0x2000
	s_movk_i32 s59, 0x1000
	s_mov_b32 s11, 0x3e47c5c2
	s_mov_b32 s15, s14
	s_mov_b32 s17, 1.0
	s_mov_b32 s16, s9
	s_movk_i32 s60, 0x5000
	s_movk_i32 s61, 0x6000
	s_movk_i32 s62, 0x7000
	s_mov_b32 s63, 0x8000
	s_mov_b32 s64, 0x9000
	s_mov_b32 s65, 0xa000
	s_mov_b32 s66, 0xb000
	s_mov_b32 s67, 0xd000
	s_mov_b32 s68, 0xe000
	s_mov_b32 s69, 0xf000
	s_mov_b32 s18, s13
	s_mov_b32 s19, s12
	s_mov_b32 s24, 0xbec3ef15
	s_mov_b32 s25, s12
	s_mov_b32 s26, 0xbf3504f3
	s_mov_b32 s27, s14
	s_mov_b32 s28, 0xbf6c835e
	s_mov_b32 s29, s13
	s_waitcnt vmcnt(0)
	s_branch .LBB0_846

; __device__ __forceinline__ float bf_lo(unsigned w) { return __uint_as_float(w << 16); }
; __device__ __forceinline__ float bf_hi(unsigned w) { return __uint_as_float(w & 0xffff0000u); }
; __device__ __forceinline__ int lnd(int x) { asm volatile("" : "+v"(x)); return x; }
; __device__ __forceinline__ void fftconv_phase(const Args& a, LAS unsigned char* lds, int bid, int G, int tid) {
;     ...
;     for (int it = vid; it < 4608; it += G) {
;         FftItem I; int r0, r1, r2, r3, f1; fft_item(it, UCT, I, r0, r1, r2, r3, f1);
;         { const int tl = lnd(tid); const f32x2v z = {0.f, 0.f};
; #pragma unroll
;           for (int k = 0; k < 4; ++k) { f32x2v s0, s1, s2, s3;
;               s0.x = pg8::bf_lo(nx[0][k]); s0.y = pg8::bf_lo(nx[1][k]); s1.x = pg8::bf_hi(nx[0][k]); s1.y = pg8::bf_hi(nx[1][k]);
;               s2.x = pg8::bf_lo(nx[2][k]); s2.y = pg8::bf_lo(nx[3][k]); s3.x = pg8::bf_hi(nx[2][k]); s3.y = pg8::bf_hi(nx[3][k]);
;               X[fft_swz(8 * tl + 2 * k)] = s0; X[fft_swz(8 * tl + 2 * k + 1)] = s1; X[fft_swz(f1 + 8 * tl + 2 * k)] = s2; X[fft_swz(f1 + 8 * tl + 2 * k + 1)] = s3; }
;           const int z0 = (f1 == 4096) ? 8192 : 4096, z1 = 12288;
; #pragma unroll
;           for (int k = 0; k < 8; ++k) { X[fft_swz(z0 + tl + 512 * k)] = z; X[fft_swz(z1 + tl + 512 * k)] = z; } }
;         { const int itn = it + G; if (itn < 4608) { FftItem J; int q0, q1, q2, q3, g1; fft_item(itn, UCT, J, q0, q1, q2, q3, g1); const int t8 = 8 * lnd(tid);
.LBB0_851:
	v_mov_b32_e32 v24, v34
	s_waitcnt vmcnt(4)
	v_lshlrev_b32_e32 v16, 16, v0
	v_lshlrev_b32_e32 v25, 3, v24
	v_lshrrev_b32_e32 v26, 2, v24
	v_bitop3_b32 v29, v26, v25, 31 bitop3:0x6c
	v_lshlrev_b32_e32 v17, 16, v4
	v_lshl_add_u32 v29, v29, 3, 0
	ds_write_b64 v29, v[16:17]
	v_or_b32_e32 v16, 1, v25
	v_bitop3_b32 v16, v26, v16, 31 bitop3:0x6c
	v_add_u32_e32 v28, s37, v25
	v_and_b32_e32 v18, 0xffff0000, v0
	v_and_b32_e32 v19, 0xffff0000, v4
	v_lshl_add_u32 v16, v16, 3, 0
	ds_write_b64 v16, v[18:19]
	v_bitop3_b32 v16, v26, v28, 31 bitop3:0x6c
	v_bfe_u32 v27, v24, 2, 5
	v_lshlrev_b32_e32 v20, 16, v8
	v_lshlrev_b32_e32 v21, 16, v12
	v_lshl_add_u32 v16, v16, 3, 0
	ds_write_b64 v16, v[20:21]
	v_bitop3_b32 v16, v28, v27, 1 bitop3:0x36
	v_or_b32_e32 v29, 2, v25
	v_and_b32_e32 v22, 0xffff0000, v8
	v_and_b32_e32 v23, 0xffff0000, v12
	v_lshl_add_u32 v16, v16, 3, 0
	v_bitop3_b32 v29, v26, v29, 31 bitop3:0x6c
	ds_write_b64 v16, v[22:23]
	v_lshlrev_b32_e32 v16, 16, v1
	v_lshlrev_b32_e32 v17, 16, v5
	v_lshl_add_u32 v29, v29, 3, 0
	ds_write_b64 v29, v[16:17]
	v_or_b32_e32 v16, 3, v25
	v_bitop3_b32 v16, v26, v16, 31 bitop3:0x6c
	v_and_b32_e32 v18, 0xffff0000, v1
	v_and_b32_e32 v19, 0xffff0000, v5
	v_lshl_add_u32 v16, v16, 3, 0
	ds_write_b64 v16, v[18:19]
	v_bitop3_b32 v16, v28, v27, 2 bitop3:0x36
	v_lshlrev_b32_e32 v20, 16, v9
	v_lshlrev_b32_e32 v21, 16, v13
	v_lshl_add_u32 v16, v16, 3, 0
	ds_write_b64 v16, v[20:21]
	v_bitop3_b32 v16, v28, v27, 3 bitop3:0x36
	v_or_b32_e32 v29, 4, v25
	v_and_b32_e32 v22, 0xffff0000, v9
	v_and_b32_e32 v23, 0xffff0000, v13
	v_lshl_add_u32 v16, v16, 3, 0
	v_bitop3_b32 v29, v26, v29, 31 bitop3:0x6c
	ds_write_b64 v16, v[22:23]
	v_lshlrev_b32_e32 v16, 16, v2
	v_lshlrev_b32_e32 v17, 16, v6
	v_lshl_add_u32 v29, v29, 3, 0
	ds_write_b64 v29, v[16:17]
	v_or_b32_e32 v16, 5, v25
	v_bitop3_b32 v16, v26, v16, 31 bitop3:0x6c
	v_and_b32_e32 v18, 0xffff0000, v2
	v_and_b32_e32 v19, 0xffff0000, v6
	v_lshl_add_u32 v16, v16, 3, 0
	ds_write_b64 v16, v[18:19]
	v_bitop3_b32 v16, v28, v27, 4 bitop3:0x36
	v_lshlrev_b32_e32 v20, 16, v10
	v_lshlrev_b32_e32 v21, 16, v14
	v_lshl_add_u32 v16, v16, 3, 0
	ds_write_b64 v16, v[20:21]
	v_bitop3_b32 v16, v28, v27, 5 bitop3:0x36
	v_or_b32_e32 v29, 6, v25
	v_and_b32_e32 v22, 0xffff0000, v10
	v_and_b32_e32 v23, 0xffff0000, v14
	v_lshl_add_u32 v16, v16, 3, 0
	v_bitop3_b32 v29, v26, v29, 31 bitop3:0x6c
	ds_write_b64 v16, v[22:23]
	v_lshlrev_b32_e32 v16, 16, v3
	v_lshlrev_b32_e32 v17, 16, v7
	v_lshl_add_u32 v29, v29, 3, 0
	ds_write_b64 v29, v[16:17]
	v_or_b32_e32 v16, 7, v25
	v_bitop3_b32 v16, v26, v16, 31 bitop3:0x6c
	v_and_b32_e32 v18, 0xffff0000, v3
	v_and_b32_e32 v19, 0xffff0000, v7
	v_lshl_add_u32 v16, v16, 3, 0
	ds_write_b64 v16, v[18:19]
	v_bitop3_b32 v16, v28, v27, 6 bitop3:0x36
	v_lshlrev_b32_e32 v20, 16, v11
	v_lshlrev_b32_e32 v21, 16, v15
	v_lshl_add_u32 v16, v16, 3, 0
	ds_write_b64 v16, v[20:21]
	v_bitop3_b32 v16, v28, v27, 7 bitop3:0x36
	v_and_b32_e32 v22, 0xffff0000, v11
	v_and_b32_e32 v23, 0xffff0000, v15
	v_lshl_add_u32 v16, v16, 3, 0
	ds_write_b64 v16, v[22:23]
	v_add_u32_e32 v16, s4, v24
	v_add_u32_e32 v17, 0x3000, v24
	v_lshrrev_b32_e32 v18, 5, v24
	v_bitop3_b32 v19, v18, v16, 31 bitop3:0x6c
	v_bitop3_b32 v17, v18, v17, 31 bitop3:0x6c
	v_lshl_add_u32 v19, v19, 3, 0
	v_lshl_add_u32 v17, v17, 3, 0
	ds_write_b64 v19, v[100:101]
	ds_write_b64 v17, v[100:101]
	v_add_u32_e32 v17, 0x200, v16
	v_lshrrev_b32_e32 v19, 5, v17
	v_bitop3_b32 v17, v19, v17, 31 bitop3:0x6c
	v_lshl_add_u32 v17, v17, 3, 0
	ds_write_b64 v17, v[100:101]
	v_add_u32_e32 v17, 0x3200, v24
	v_lshrrev_b32_e32 v19, 5, v17
	v_bitop3_b32 v17, v19, v17, 31 bitop3:0x6c
	v_lshl_add_u32 v17, v17, 3, 0
	ds_write_b64 v17, v[100:101]
	v_add_u32_e32 v17, 0x400, v16
	v_bitop3_b32 v17, v18, v17, 31 bitop3:0x6c
	v_lshl_add_u32 v17, v17, 3, 0
	ds_write_b64 v17, v[100:101]
	v_add_u32_e32 v17, 0x3400, v24
	v_bitop3_b32 v17, v18, v17, 31 bitop3:0x6c
	v_lshl_add_u32 v17, v17, 3, 0
	ds_write_b64 v17, v[100:101]
	v_add_u32_e32 v17, 0x600, v16
	v_lshrrev_b32_e32 v19, 5, v17
	v_bitop3_b32 v17, v19, v17, 31 bitop3:0x6c
	v_lshl_add_u32 v17, v17, 3, 0
	ds_write_b64 v17, v[100:101]
	v_add_u32_e32 v17, 0x3600, v24
	v_lshrrev_b32_e32 v19, 5, v17
	v_bitop3_b32 v17, v19, v17, 31 bitop3:0x6c
	v_lshl_add_u32 v17, v17, 3, 0
	ds_write_b64 v17, v[100:101]
	v_add_u32_e32 v17, 0x800, v16
	v_bitop3_b32 v17, v18, v17, 31 bitop3:0x6c
	v_lshl_add_u32 v17, v17, 3, 0
	ds_write_b64 v17, v[100:101]
	v_add_u32_e32 v17, 0x3800, v24
	v_bitop3_b32 v17, v18, v17, 31 bitop3:0x6c
	v_lshl_add_u32 v17, v17, 3, 0
	ds_write_b64 v17, v[100:101]
	v_add_u32_e32 v17, 0xa00, v16
	v_lshrrev_b32_e32 v19, 5, v17
	v_bitop3_b32 v17, v19, v17, 31 bitop3:0x6c
	v_lshl_add_u32 v17, v17, 3, 0
	ds_write_b64 v17, v[100:101]
	v_add_u32_e32 v17, 0x3a00, v24
	v_lshrrev_b32_e32 v19, 5, v17
	v_bitop3_b32 v17, v19, v17, 31 bitop3:0x6c
	v_lshl_add_u32 v17, v17, 3, 0
	ds_write_b64 v17, v[100:101]
	v_add_u32_e32 v17, 0xc00, v16
	v_bitop3_b32 v17, v18, v17, 31 bitop3:0x6c
	v_lshl_add_u32 v17, v17, 3, 0
	ds_write_b64 v17, v[100:101]
	v_add_u32_e32 v17, 0x3c00, v24
	v_bitop3_b32 v17, v18, v17, 31 bitop3:0x6c
	v_lshl_add_u32 v17, v17, 3, 0
	v_add_u32_e32 v16, 0xe00, v16
	ds_write_b64 v17, v[100:101]
	v_lshrrev_b32_e32 v17, 5, v16
	v_bitop3_b32 v16, v17, v16, 31 bitop3:0x6c
	v_lshl_add_u32 v16, v16, 3, 0
	ds_write_b64 v16, v[100:101]
	v_add_u32_e32 v16, 0x3e00, v24
	s_add_i32 s46, s46, s70
	v_lshrrev_b32_e32 v17, 5, v16
	s_cmpk_gt_i32 s46, 0x11ff
	v_bitop3_b32 v16, v17, v16, 31 bitop3:0x6c
	s_cselect_b64 s[48:49], -1, 0
	v_lshl_add_u32 v16, v16, 3, 0
	s_and_b64 vcc, exec, s[48:49]
	ds_write_b64 v16, v[100:101]
	s_cbranch_vccnz .LBB0_857
	s_cmpk_gt_i32 s46, 0xbff
	s_mov_b64 s[44:45], -1
	s_cbranch_scc0 .LBB0_854
	s_add_i32 s1, s46, 0xfffff400
	s_lshr_b32 s8, s1, 1
	s_add_i32 s1, s54, s47
	s_and_b32 s1, s1, 0x4000
	s_or_b32 s5, s1, 0x10000
	s_or_b32 s22, s1, 0x11000
	s_or_b32 s20, s1, 0x12000
	s_or_b32 s4, s1, 0x13000
	s_mov_b64 s[44:45], 0
	s_mov_b64 s[34:35], s[8:9]
	s_mov_b32 s8, s5
